# P6 tile loop: LDS writes drained before barrier 1 and the second per-half-step barrier removed (V buffer is next read only after the following barrier 1; rescale scratch is wave-private); exit path ke
# speedup vs baseline: 1.0029x; 1.0029x over previous
.LBB0_1374:
	s_waitcnt vmcnt(2)
	ds_write_b128 v223, v[10:13] offset:32768
	ds_write_b128 v223, v[208:211] offset:40960
	s_waitcnt lgkmcnt(0)
	s_barrier
	s_waitcnt vmcnt(0)
	v_cmp_gt_f32_e32 vcc, 1.0, v14
	ds_write_b128 v235, v[2:5]
	ds_write_b128 v235, v[6:9] offset:8192
	s_cbranch_vccz .LBB0_1378
	s_and_saveexec_b64 s[6:7], s[2:3]
	ds_write_b32 v225, v14 offset:128
	s_or_b64 exec, exec, s[6:7]
	s_waitcnt lgkmcnt(0)
	ds_read_b128 v[144:147], v224 offset:224
	ds_read_b128 v[148:151], v224 offset:192
	ds_read_b128 v[152:155], v224 offset:160
	ds_read_b128 v[156:159], v224 offset:128
	s_waitcnt lgkmcnt(3)
	v_pk_mul_f32 v[78:79], v[78:79], v[146:147]
	s_waitcnt lgkmcnt(2)
	v_pk_mul_f32 v[74:75], v[74:75], v[150:151]
	s_waitcnt lgkmcnt(1)
	v_pk_mul_f32 v[70:71], v[70:71], v[154:155]
	s_waitcnt lgkmcnt(0)
	v_pk_mul_f32 v[66:67], v[66:67], v[158:159]
	v_pk_mul_f32 v[76:77], v[76:77], v[144:145]
	v_pk_mul_f32 v[72:73], v[72:73], v[148:149]
	v_pk_mul_f32 v[68:69], v[68:69], v[152:153]
	v_pk_mul_f32 v[64:65], v[64:65], v[156:157]
	v_pk_mul_f32 v[62:63], v[62:63], v[146:147]
	v_pk_mul_f32 v[58:59], v[58:59], v[150:151]
	v_pk_mul_f32 v[54:55], v[54:55], v[154:155]
	v_pk_mul_f32 v[50:51], v[50:51], v[158:159]
	v_pk_mul_f32 v[60:61], v[60:61], v[144:145]
	v_pk_mul_f32 v[56:57], v[56:57], v[148:149]
	v_pk_mul_f32 v[52:53], v[52:53], v[152:153]
	v_pk_mul_f32 v[48:49], v[48:49], v[156:157]
	v_pk_mul_f32 v[46:47], v[46:47], v[146:147]
	v_pk_mul_f32 v[42:43], v[42:43], v[150:151]
	v_pk_mul_f32 v[38:39], v[38:39], v[154:155]
	v_pk_mul_f32 v[34:35], v[34:35], v[158:159]
	v_pk_mul_f32 v[44:45], v[44:45], v[144:145]
	v_pk_mul_f32 v[40:41], v[40:41], v[148:149]
	v_pk_mul_f32 v[36:37], v[36:37], v[152:153]
	v_pk_mul_f32 v[32:33], v[32:33], v[156:157]
	v_pk_mul_f32 v[30:31], v[30:31], v[146:147]
	v_pk_mul_f32 v[26:27], v[26:27], v[150:151]
	v_pk_mul_f32 v[22:23], v[22:23], v[154:155]
	v_pk_mul_f32 v[18:19], v[18:19], v[158:159]
	v_pk_mul_f32 v[28:29], v[28:29], v[144:145]
	v_pk_mul_f32 v[24:25], v[24:25], v[148:149]
	v_pk_mul_f32 v[20:21], v[20:21], v[152:153]
	v_pk_mul_f32 v[16:17], v[16:17], v[156:157]
.LBB0_1378:
	s_add_i32 s7, s96, -1
	s_and_b32 s6, s7, 31
	s_cmp_lg_u32 s6, 0
	s_waitcnt lgkmcnt(0)
	s_cbranch_scc1 .LBB0_1380
	s_lshr_b32 s7, s7, 3
	v_add_u32_e32 v0, s7, v236
	ds_read_b32 v222, v0

.Lselb_nokw:
	s_waitcnt lgkmcnt(0)
	s_barrier
	s_cbranch_vccnz .LBB0_1428
	s_waitcnt vmcnt(0)
	ds_write_b128 v235, v[2:5] offset:16384
	ds_write_b128 v235, v[6:9] offset:24576

; template <int MODE>
; __device__ __forceinline__ void attn_block(const BlockRef& cur, const BlockRef& nxt, char* lds, Seam& S, int par, const int wid) {
;     ...
;     for (int t = 1; t + 1 < NT; t += 2) {
;         HALF_STEP(pB0, pB1, mnB, alB, actB, bitB, pA0, pA1, alA, actA, t, 1, 0, 0);
;         HALF_STEP(pA0, pA1, mnA, alA, actA, bitA, pB0, pB1, alB, actB, t + 1, 0, 1, 1);
;     }
.LBB0_1432:
	s_addk_i32 s95, 0x80
	s_add_i32 s4, s96, 2
	s_add_i32 s5, s96, 1
	s_mov_b64 s[6:7], 0x8000
	v_add_u32_e32 v237, 0xfffffe00, v237
	v_add_u32_e32 v238, 0xffffff80, v238
	s_cmp_gt_u32 s5, s47
	v_lshl_add_u64 v[214:215], v[214:215], 0, s[6:7]
	s_waitcnt lgkmcnt(0)
	s_cbranch_scc1 .Lselb_exit
	s_mov_b32 s96, s4
	s_add_i32 s5, s96, -2
	s_and_b32 s4, s5, 31
	s_cmp_lg_u32 s4, 0
	s_cbranch_scc1 .LBB0_1330
	s_branch .LBB0_1329
.Lselb_exit:
	s_barrier
	s_branch .LBB0_1435
